# speedup vs baseline: 1.0045x; 1.0045x over previous
; __global__ void __launch_bounds__(512, 2) mega(Params P) {
;     ...
;     xcd_barrier(xb);
;     {
;       if ((bid & 7) < 2 && (bid >> 3) < 8) {
;           const int which = bid & 1, mt_ = bid >> 3;
;           const int m0 = mt_ * 128;
;           u16* hid = which ? HIDV : HIDK;
;           const float* b1 = BIAS1 + which * 256;
;           for (int nt_ = 0; nt_ < 2; ++nt_) {
.LBB0_364:
	s_or_b64 exec, exec, s[26:27]
	v_readlane_b32 s10, v253, 51
	v_readlane_b32 s11, v253, 52
	s_andn2_b64 vcc, exec, s[10:11]
	s_waitcnt lgkmcnt(0)
	s_barrier
	v_readfirstlane_b32 s100, v159
	s_nop 3
	s_cmp_ge_u32 s100, 0x100
	s_cbranch_scc0 .Lmy_prio_done
	s_setprio 1
.Lmy_prio_done:
	s_cbranch_vccnz .LBB0_675
	s_mov_b32 s2, 0
	s_mov_b64 s[30:31], -1
	s_branch .LBB0_367

; __global__ void __launch_bounds__(512, 2) mega(Params P) {
;     ...
;     xcd_barrier(xb);
;     {
;       for (int k_ = 0;; ++k_) {
;         int pm, pn;
;         if (!gemm256_tile_of((int)blockIdx.x, (int)gridDim.x, k_, 4, pm, pn)) break;
.LBB0_1249:
	s_or_b64 exec, exec, s[26:27]
	s_mov_b32 s2, 0
	s_waitcnt lgkmcnt(0)
	s_barrier
	s_setprio 0
	s_branch .LBB0_1252
